# v091 + layer-1 adaLN GEMV done early: 2 units per retention workgroup in layer 0's mixer phase + 1 unit per workgroup 192..255 in layer 0's modulation phase
# speedup vs baseline: 1.0014x; 1.0014x over previous
.Lmy_a_entry:
	s_waitcnt vmcnt(0)
	v_mov_b32_e32 v8, v0
	s_mov_b64 s[6:7], s[70:71]
	s_load_dwordx2 s[4:5], s[6:7], 0xe0
	v_readlane_b32 s8, v253, 3
	v_readfirstlane_b32 s0, v8
	v_readlane_b32 s9, v253, 4
	v_and_b32_e32 v16, 63, v8
	s_cmp_eq_u32 s100, 1
	s_cbranch_scc1 .Lmy_a_zero
	s_cmp_eq_u32 s100, 0
	s_cbranch_scc0 .Lmy_a_keep
	s_cmpk_lg_i32 s3, 0x100
	s_cbranch_scc1 .Lmy_a_keep
	v_readlane_b32 s2, v255, 8
	s_nop 3
	s_cmp_eq_u32 s2, 1
	s_cbranch_scc1 .Lmy_a_zero
	s_cmpk_lt_i32 s76, 0xc0
	s_cbranch_scc1 .Lmy_a_keep
	s_mov_b32 s100, 4
	s_add_i32 s101, s76, 0xffffffc0
	s_mov_b32 s2, 1
	v_writelane_b32 v255, s2, 8
	s_mov_b64 s[8:9], exec
	s_branch .Lmy_a_keep

.Lmy_a_keep:
	s_andn2_b64 vcc, exec, s[8:9]
	s_ashr_i32 s30, s0, 6
	s_cbranch_vccnz .LBB0_37
	v_ashrrev_i32_e32 v2, 31, v8
	v_lshrrev_b32_e32 v2, 26, v2
	s_waitcnt lgkmcnt(0)
	v_readlane_b32 s12, v255, 8
	v_add_u32_e32 v2, v8, v2
	s_load_dwordx4 s[48:51], s[6:7], 0x28
	s_load_dwordx2 s[8:9], s[6:7], 0x8
	s_load_dwordx2 s[10:11], s[6:7], 0x18
	s_mov_b32 s42, s12
	v_ashrrev_i32_e32 v6, 6, v2
	v_and_b32_e32 v2, 0xffffffc0, v2
	v_mad_u64_u32 v[4:5], s[42:43], s42, 5, v[6:7]
	s_mul_i32 s0, s12, 0xc000
	v_sub_u32_e32 v2, v8, v2
	s_waitcnt lgkmcnt(0)
	v_mov_b64_e32 v[10:11], s[4:5]
	s_mov_b32 s42, 0xc000
	v_readlane_b32 s13, v255, 9
	s_mul_i32 s46, s12, 0xc000000
	s_add_u32 s12, s50, s0
	v_ashrrev_i32_e32 v3, 31, v2
	v_mad_i64_i32 v[4:5], s[42:43], v4, s42, v[10:11]
	s_addc_u32 s13, s51, 0
	s_movk_i32 s0, 0x5000
	s_lshl_b32 s2, s30, 11
	s_mul_i32 s40, s30, 0x500
	v_lshl_add_u64 v[4:5], v[2:3], 2, v[4:5]
	v_max_i32_e32 v3, 0x4e00, v8
	v_cmp_gt_i32_e64 s[38:39], s0, v8
	s_lshl_b32 s0, s30, 9
	s_add_i32 s2, s2, 0
	s_add_i32 s40, s14, s40
	v_sub_u32_e32 v3, v3, v8
	s_mul_i32 s47, s30, 0x1800000
	v_add_u32_e32 v3, 0x1ff, v3
	s_mul_hi_i32 s0, s0, 0xc000
	s_add_u32 s46, s46, s47
	v_lshlrev_b32_e32 v10, 8, v6
	v_lshrrev_b32_e32 v6, 9, v3
	s_addc_u32 s0, 0, s0
	s_mov_b64 s[42:43], 0xaf40000
	v_add_u32_e32 v6, 1, v6
	s_add_u32 s46, s48, s46
	v_lshlrev_b32_e32 v194, 2, v16
	v_lshl_add_u64 v[4:5], v[4:5], 0, s[42:43]
	v_cmp_lt_u32_e64 s[42:43], s15, v3
	v_and_b32_e32 v3, 0xfffffe, v6
	s_addc_u32 s47, s49, s0
	v_add_u32_e32 v17, s40, v194
	s_movk_i32 s40, 0x140
	v_lshl_add_u32 v12, v2, 2, s14
	v_cmp_ne_u32_e64 s[44:45], v6, v3
	v_lshl_add_u64 v[6:7], s[46:47], 0, v[194:195]
	s_mov_b64 s[46:47], 0x54000
	v_readlane_b32 s0, v254, 30
	v_cmp_gt_i32_e64 s[40:41], s40, v8
	v_lshl_add_u32 v18, v3, 9, v8
	v_add_u32_e32 v9, 0x200, v8
	v_lshl_add_u32 v19, v8, 2, 0
	v_lshl_add_u64 v[6:7], v[6:7], 0, s[46:47]
	s_mov_b64 s[46:47], 0
	v_add_u32_e32 v20, v12, v10
	s_mov_b32 s48, s0
	s_mov_b32 s56, s76
	s_cmp_ge_u32 s100, 3
	s_cbranch_scc0 .Lmy_g_nou
	s_mov_b32 s56, s101
	s_lshl_b32 s48, s101, 6

.LBB0_37:
	s_cmp_eq_u32 s100, 3
	s_cbranch_scc1 .Lmy_tr_dret
	s_cmp_eq_u32 s100, 4
	s_cbranch_scc0 .Lmy_a_m4done
	s_mov_b32 s100, 0
	s_mov_b32 s0, 0
	v_writelane_b32 v255, s0, 8
	s_nop 1

.Lpb_next:
	s_add_i32 s65, s65, s3
	s_cmpk_lt_i32 s65, 0x440
	s_cbranch_scc1 .Lpb_loop
	s_branch .LBB0_178
	s_nop 0
	s_nop 0
	s_nop 0
	s_nop 0
	s_nop 0
	s_nop 0
	s_nop 0
	s_nop 0
	s_nop 0
	s_nop 0
	s_nop 0
	s_nop 0
	s_nop 0
	s_nop 0
	s_nop 0
	s_nop 0
	s_nop 0
	s_nop 0
	s_nop 0
	s_nop 0
	s_nop 0
	s_branch .LBB0_178
	s_nop 0
	s_nop 0
	s_nop 0
	s_nop 0
	s_nop 0
	s_nop 0
	s_nop 0
	s_nop 0
	s_nop 0
	s_nop 0
	s_nop 0
	s_nop 0
	s_nop 0
	s_nop 0
	s_nop 0
	s_nop 0
	s_nop 0
	s_nop 0
	s_nop 0
	s_nop 0
	s_nop 0
	s_nop 0
	s_nop 0
	s_nop 0
	s_nop 0
	s_nop 0
	s_nop 0
	s_nop 0
	s_nop 0
	s_nop 0
	s_nop 0
	s_nop 0
	s_nop 0
	s_nop 0
	s_nop 0
	s_nop 0
	s_nop 0
	s_nop 0
	s_nop 0
	s_nop 0
	s_nop 0
	s_nop 0
	s_nop 0
	s_nop 0
	s_nop 0
	s_nop 0
	s_nop 0

.Lmy_d_ret:
	s_add_i32 s101, s101, 64
	s_cmpk_lt_i32 s101, 0x80
	s_cbranch_scc1 .Lmy_d_loop
	s_mov_b32 s100, 0
	s_mov_b32 s0, 0
	v_writelane_b32 v255, s0, 8
	s_nop 1
